# PH1 tail: KTAB reduction issues two iterations of loads per drain; W2 bbar rows loaded together
# baseline (speedup 1.0000x reference)
; __device__ __forceinline__ f32x2 cmul(f32x2 a, f32x2 b) { return (f32x2){a.x * b.x - a.y * b.y, a.x * b.y + a.y * b.x}; }
; __global__ void __launch_bounds__(512, 2) fwd_kernel(Args a) {
;     ...
;         for (size_t i = vt; i < (size_t)NG * 16 * 64; i += VNT) {
;             const int hq = (int)i & 3, h = ((int)i >> 2) & 15, lag = ((int)i >> 6) & 15, g = (int)i >> 10;
;             float s0 = 0.f, s1 = 0.f, s2 = 0.f, s3 = 0.f;
;             const float* crp = c_re + (size_t)(g * NH + h) * NP; const float* cip = c_im + (size_t)(g * NH + h) * NP;
; #pragma unroll 8
;             for (int p = 0; p < NP; ++p) {
;                 const int gp = g * NP + p;
;                 const f32x2 ac = cmul(APW[gp * 17 + lag], (f32x2){crp[p], cip[p]});
;                 const f32x4 b01 = *(const f32x4*)(BBAR + (size_t)gp * NH + 4 * hq), b23 = *(const f32x4*)(BBAR + (size_t)gp * NH + 4 * hq + 2);
;                 s0 += ac.x * b01[0] - ac.y * b01[1]; s1 += ac.x * b01[2] - ac.y * b01[3]; s2 += ac.x * b23[0] - ac.y * b23[1]; s3 += ac.x * b23[2] - ac.y * b23[3];
;             }
.LBB0_198:
	v_lshl_add_u64 v[24:25], s[20:21], 0, v[22:23]
	v_lshl_add_u64 v[26:27], v[18:19], 0, s[8:9]
	v_lshl_add_u64 v[28:29], v[20:21], 0, s[8:9]
	v_lshl_add_u64 v[30:31], s[20:21], 0, v[14:15]
	v_add_u32_e32 v4, 0xffffff9a, v16
	v_mov_b32_e32 v17, v5
	global_load_dwordx4 v[36:39], v[26:27], off
	global_load_dwordx4 v[40:43], v[28:29], off
	global_load_dwordx4 v[44:47], v[26:27], off offset:16
	s_nop 0
	global_load_dwordx4 v[26:29], v[28:29], off offset:16
	s_nop 0
	global_load_dwordx2 v[24:25], v[24:25], off
	v_add_co_u32_e32 v104, vcc, s0, v30
	v_lshl_add_u64 v[56:57], v[4:5], 3, s[16:17]
	v_add_u32_e32 v4, 0xffffffab, v16
	v_lshl_add_u64 v[52:53], v[30:31], 0, s[44:45]
	v_addc_co_u32_e32 v105, vcc, 0, v31, vcc
	v_lshl_add_u64 v[60:61], v[30:31], 0, s[46:47]
	v_lshl_add_u64 v[68:69], v[30:31], 0, s[48:49]
	v_lshl_add_u64 v[76:77], v[30:31], 0, s[50:51]
	v_lshl_add_u64 v[84:85], v[30:31], 0, s[52:53]
	v_lshl_add_u64 v[92:93], v[30:31], 0, s[54:55]
	v_lshl_add_u64 v[100:101], v[30:31], 0, s[56:57]
	v_lshl_add_u64 v[106:107], v[16:17], 3, s[16:17]
	v_lshl_add_u64 v[30:31], v[30:31], 0, s[58:59]
	v_lshl_add_u64 v[114:115], v[4:5], 3, s[16:17]
	v_add_u32_e32 v4, 0xffffffbc, v16
	global_load_dwordx4 v[48:51], v[104:105], off
	s_nop 0
	global_load_dwordx4 v[52:55], v[52:53], off offset:16
	s_nop 0
	global_load_dwordx2 v[112:113], v[56:57], off
	s_nop 0
	global_load_dwordx4 v[56:59], v[104:105], off offset:128
	s_nop 0
	global_load_dwordx4 v[60:63], v[60:61], off offset:16
	s_nop 0
	global_load_dwordx4 v[64:67], v[104:105], off offset:256
	s_nop 0
	global_load_dwordx4 v[68:71], v[68:69], off offset:16
	s_nop 0
	global_load_dwordx4 v[72:75], v[104:105], off offset:384
	s_nop 0
	global_load_dwordx4 v[76:79], v[76:77], off offset:16
	s_nop 0
	global_load_dwordx4 v[80:83], v[104:105], off offset:512
	s_nop 0
	global_load_dwordx4 v[84:87], v[84:85], off offset:16
	s_add_u32 s8, s8, 32
	global_load_dwordx4 v[88:91], v[104:105], off offset:640
	s_nop 0
	global_load_dwordx4 v[92:95], v[92:93], off offset:16
	s_nop 0
	global_load_dwordx4 v[96:99], v[104:105], off offset:768
	s_nop 0
	global_load_dwordx4 v[100:103], v[100:101], off offset:16
	s_nop 0
	global_load_dwordx2 v[116:117], v[106:107], off
	s_nop 0
	global_load_dwordx4 v[104:107], v[104:105], off offset:896
	s_nop 0
	global_load_dwordx4 v[108:111], v[30:31], off offset:16
	s_addc_u32 s9, s9, 0
	global_load_dwordx2 v[30:31], v[114:115], off
	v_lshl_add_u64 v[114:115], v[4:5], 3, s[16:17]
	v_subrev_u32_e32 v4, 51, v16
	global_load_dwordx2 v[114:115], v[114:115], off
	v_lshl_add_u64 v[118:119], v[4:5], 3, s[16:17]
	v_subrev_u32_e32 v4, 34, v16
	global_load_dwordx2 v[118:119], v[118:119], off
	v_lshl_add_u64 v[120:121], v[4:5], 3, s[16:17]
	v_subrev_u32_e32 v4, 17, v16
	global_load_dwordx2 v[120:121], v[120:121], off
	v_lshl_add_u64 v[122:123], v[4:5], 3, s[16:17]
	global_load_dwordx2 v[122:123], v[122:123], off
	v_lshl_add_u64 v[14:15], v[14:15], 0, s[60:61]
	v_lshl_add_u64 v[22:23], v[22:23], 0, s[62:63]
	s_cmpk_eq_i32 s8, 0x100
	v_add_u32_e32 v16, 0x88, v16
	v_lshl_add_u64 v[144:145], s[20:21], 0, v[22:23]
	v_lshl_add_u64 v[146:147], v[18:19], 0, s[8:9]
	v_lshl_add_u64 v[148:149], v[20:21], 0, s[8:9]
	v_lshl_add_u64 v[150:151], s[20:21], 0, v[14:15]
	v_add_u32_e32 v4, 0xffffff9a, v16
	v_mov_b32_e32 v17, v5
	global_load_dwordx4 v[158:161], v[146:147], off
	global_load_dwordx4 v[162:165], v[148:149], off
	global_load_dwordx4 v[166:169], v[146:147], off offset:16
	s_nop 0
	global_load_dwordx4 v[146:149], v[148:149], off offset:16
	s_nop 0
	global_load_dwordx2 v[144:145], v[144:145], off
	v_add_co_u32_e32 v226, vcc, s0, v150
	v_lshl_add_u64 v[178:179], v[4:5], 3, s[16:17]
	v_add_u32_e32 v4, 0xffffffab, v16
	v_lshl_add_u64 v[174:175], v[150:151], 0, s[44:45]
	v_addc_co_u32_e32 v227, vcc, 0, v151, vcc
	v_lshl_add_u64 v[182:183], v[150:151], 0, s[46:47]
	v_lshl_add_u64 v[190:191], v[150:151], 0, s[48:49]
	v_lshl_add_u64 v[198:199], v[150:151], 0, s[50:51]
	v_lshl_add_u64 v[206:207], v[150:151], 0, s[52:53]
	v_lshl_add_u64 v[214:215], v[150:151], 0, s[54:55]
	v_lshl_add_u64 v[222:223], v[150:151], 0, s[56:57]
	v_lshl_add_u64 v[228:229], v[16:17], 3, s[16:17]
	v_lshl_add_u64 v[150:151], v[150:151], 0, s[58:59]
	v_lshl_add_u64 v[238:239], v[4:5], 3, s[16:17]
	v_add_u32_e32 v4, 0xffffffbc, v16
	global_load_dwordx4 v[170:173], v[226:227], off
	s_nop 0
	global_load_dwordx4 v[174:177], v[174:175], off offset:16
	s_nop 0
	global_load_dwordx2 v[234:235], v[178:179], off
	s_nop 0
	global_load_dwordx4 v[178:181], v[226:227], off offset:128
	s_nop 0
	global_load_dwordx4 v[182:185], v[182:183], off offset:16
	s_nop 0
	global_load_dwordx4 v[186:189], v[226:227], off offset:256
	s_nop 0
	global_load_dwordx4 v[190:193], v[190:191], off offset:16
	s_nop 0
	global_load_dwordx4 v[194:197], v[226:227], off offset:384
	s_nop 0
	global_load_dwordx4 v[198:201], v[198:199], off offset:16
	s_nop 0
	global_load_dwordx4 v[202:205], v[226:227], off offset:512
	s_nop 0
	global_load_dwordx4 v[206:209], v[206:207], off offset:16
	s_add_u32 s8, s8, 32
	global_load_dwordx4 v[210:213], v[226:227], off offset:640
	s_nop 0
	global_load_dwordx4 v[214:217], v[214:215], off offset:16
	s_nop 0
	global_load_dwordx4 v[218:221], v[226:227], off offset:768
	s_nop 0
	global_load_dwordx4 v[222:225], v[222:223], off offset:16
	s_nop 0
	global_load_dwordx2 v[240:241], v[228:229], off
	s_nop 0
	global_load_dwordx4 v[226:229], v[226:227], off offset:896
	s_nop 0
	global_load_dwordx4 v[230:233], v[150:151], off offset:16
	s_addc_u32 s9, s9, 0
	global_load_dwordx2 v[150:151], v[238:239], off
	v_lshl_add_u64 v[238:239], v[4:5], 3, s[16:17]
	v_subrev_u32_e32 v4, 51, v16
	global_load_dwordx2 v[238:239], v[238:239], off
	v_lshl_add_u64 v[242:243], v[4:5], 3, s[16:17]
	v_subrev_u32_e32 v4, 34, v16
	global_load_dwordx2 v[242:243], v[242:243], off
	v_lshl_add_u64 v[244:245], v[4:5], 3, s[16:17]
	v_subrev_u32_e32 v4, 17, v16
	global_load_dwordx2 v[244:245], v[244:245], off
	v_lshl_add_u64 v[246:247], v[4:5], 3, s[16:17]
	global_load_dwordx2 v[246:247], v[246:247], off
	v_lshl_add_u64 v[14:15], v[14:15], 0, s[60:61]
	v_lshl_add_u64 v[22:23], v[22:23], 0, s[62:63]
	s_cmpk_eq_i32 s8, 0x100
	v_add_u32_e32 v16, 0x88, v16
	s_waitcnt vmcnt(0)
; __device__ __forceinline__ f32x2 cmul(f32x2 a, f32x2 b) { return (f32x2){a.x * b.x - a.y * b.y, a.x * b.y + a.y * b.x}; }
; __global__ void __launch_bounds__(512, 2) fwd_kernel(Args a) {
;     ...
;             for (int p = 0; p < NP; ++p) {
;                 const int gp = g * NP + p;
;                 const f32x2 ac = cmul(APW[gp * 17 + lag], (f32x2){crp[p], cip[p]});
;                 const f32x4 b01 = *(const f32x4*)(BBAR + (size_t)gp * NH + 4 * hq), b23 = *(const f32x4*)(BBAR + (size_t)gp * NH + 4 * hq + 2);
;                 s0 += ac.x * b01[0] - ac.y * b01[1]; s1 += ac.x * b01[2] - ac.y * b01[3]; s2 += ac.x * b23[0] - ac.y * b23[1]; s3 += ac.x * b23[2] - ac.y * b23[3];
;             }
	v_mov_b32_e32 v124, v36
	v_mov_b32_e32 v125, v40
	v_mov_b32_e32 v126, v40
	v_mov_b32_e32 v127, v36
	v_mov_b32_e32 v36, v41
	v_pk_mul_f32 v[124:125], v[24:25], v[124:125]
	v_pk_mul_f32 v[24:25], v[24:25], v[126:127]
	v_mov_b32_e32 v40, v37
	v_mov_b32_e32 v132, v38
	v_mov_b32_e32 v133, v42
	v_mov_b32_e32 v134, v42
	v_mov_b32_e32 v135, v38
	v_mov_b32_e32 v127, v48
	v_mov_b32_e32 v48, v51
	v_mov_b32_e32 v51, v52
	v_mov_b32_e32 v52, v55
	v_pk_mul_f32 v[36:37], v[112:113], v[36:37]
	v_pk_add_f32 v[24:25], v[24:25], v[24:25] op_sel:[1,0] op_sel_hi:[1,0]
	v_mov_b32_e32 v38, v43
	v_mov_b32_e32 v140, v46
	v_mov_b32_e32 v143, v46
	v_mov_b32_e32 v46, v29
	v_mov_b32_e32 v126, v50
	v_mov_b32_e32 v50, v54
	v_pk_mul_f32 v[40:41], v[112:113], v[40:41]
	v_mov_b32_e32 v54, v58
	v_mov_b32_e32 v55, v56
	v_mov_b32_e32 v56, v59
	v_mov_b32_e32 v58, v62
	v_mov_b32_e32 v59, v60
	v_mov_b32_e32 v60, v63
	v_mov_b32_e32 v62, v66
	v_mov_b32_e32 v63, v64
	v_mov_b32_e32 v64, v67
	v_mov_b32_e32 v66, v70
	v_mov_b32_e32 v67, v68
	v_mov_b32_e32 v68, v71
	v_mov_b32_e32 v70, v74
	v_mov_b32_e32 v71, v72
	v_mov_b32_e32 v72, v75
	v_mov_b32_e32 v74, v78
	v_mov_b32_e32 v75, v76
	v_mov_b32_e32 v76, v79
	v_mov_b32_e32 v78, v82
	v_mov_b32_e32 v79, v80
	v_mov_b32_e32 v80, v83
	v_mov_b32_e32 v82, v86
	v_mov_b32_e32 v83, v84
	v_mov_b32_e32 v84, v87
	v_mov_b32_e32 v86, v90
	v_mov_b32_e32 v87, v88
	v_mov_b32_e32 v88, v91
	v_mov_b32_e32 v90, v94
	v_mov_b32_e32 v91, v92
	v_mov_b32_e32 v92, v95
	v_mov_b32_e32 v94, v98
	v_mov_b32_e32 v95, v96
	v_mov_b32_e32 v96, v99
	v_mov_b32_e32 v98, v102
	v_mov_b32_e32 v99, v100
	v_mov_b32_e32 v100, v103
	v_mov_b32_e32 v102, v106
	v_mov_b32_e32 v103, v104
	v_mov_b32_e32 v104, v107
	v_mov_b32_e32 v106, v110
	v_mov_b32_e32 v107, v108
	v_mov_b32_e32 v108, v111
	v_pk_add_f32 v[110:111], v[124:125], v[124:125] op_sel:[0,1] op_sel_hi:[0,1] neg_lo:[0,1] neg_hi:[0,1]
	v_pk_add_f32 v[36:37], v[36:37], v[36:37] op_sel:[1,0] op_sel_hi:[1,0]
	v_pk_mul_f32 v[112:113], v[30:31], v[132:133]
	v_pk_mul_f32 v[30:31], v[30:31], v[134:135]
	v_pk_mul_f32 v[48:49], v[24:25], v[48:49]
	v_pk_mul_f32 v[24:25], v[24:25], v[52:53]
	v_mov_b32_e32 v42, v39
	v_mov_b32_e32 v138, v26
	v_mov_b32_e32 v139, v44
	v_mov_b32_e32 v141, v28
	v_mov_b32_e32 v142, v28
	v_mov_b32_e32 v28, v47
	v_pk_mul_f32 v[46:47], v[116:117], v[46:47]
	v_pk_add_f32 v[40:41], v[40:41], v[40:41] op_sel:[0,1] op_sel_hi:[0,1] neg_lo:[0,1] neg_hi:[0,1]
	v_pk_mul_f32 v[52:53], v[36:37], v[56:57]
	v_pk_mul_f32 v[36:37], v[36:37], v[60:61]
	v_pk_add_f32 v[30:31], v[30:31], v[30:31] op_sel:[1,0] op_sel_hi:[1,0]
	v_pk_mul_f32 v[38:39], v[114:115], v[38:39]
	v_pk_fma_f32 v[48:49], v[110:111], v[126:127], v[48:49] neg_lo:[0,0,1] neg_hi:[0,0,1]
	v_pk_fma_f32 v[24:25], v[110:111], v[50:51], v[24:25] neg_lo:[0,0,1] neg_hi:[0,0,1]
	v_mov_b32_e32 v136, v44
	v_mov_b32_e32 v137, v26
	v_mov_b32_e32 v44, v27
	v_pk_mul_f32 v[28:29], v[116:117], v[28:29]
	v_pk_add_f32 v[46:47], v[46:47], v[46:47] op_sel:[1,0] op_sel_hi:[1,0]
	v_pk_add_f32 v[56:57], v[112:113], v[112:113] op_sel:[0,1] op_sel_hi:[0,1] neg_lo:[0,1] neg_hi:[0,1]
	v_pk_mul_f32 v[42:43], v[114:115], v[42:43]
	v_pk_fma_f32 v[50:51], v[40:41], v[54:55], v[52:53] neg_lo:[0,0,1] neg_hi:[0,0,1]
	v_pk_fma_f32 v[36:37], v[40:41], v[58:59], v[36:37] neg_lo:[0,0,1] neg_hi:[0,0,1]
	v_pk_mul_f32 v[40:41], v[30:31], v[64:65]
	v_pk_mul_f32 v[30:31], v[30:31], v[68:69]
	v_pk_add_f32 v[38:39], v[38:39], v[38:39] op_sel:[1,0] op_sel_hi:[1,0]
	v_pk_mul_f32 v[54:55], v[118:119], v[138:139]
	v_pk_add_f32 v[12:13], v[12:13], v[48:49]
	v_pk_add_f32 v[10:11], v[10:11], v[24:25]
	v_mov_b32_e32 v26, v45
	v_pk_add_f32 v[28:29], v[28:29], v[28:29] op_sel:[0,1] op_sel_hi:[0,1] neg_lo:[0,1] neg_hi:[0,1]
	v_pk_mul_f32 v[60:61], v[46:47], v[104:105]
	v_pk_mul_f32 v[46:47], v[46:47], v[108:109]
	v_pk_add_f32 v[42:43], v[42:43], v[42:43] op_sel:[0,1] op_sel_hi:[0,1] neg_lo:[0,1] neg_hi:[0,1]
	v_pk_mul_f32 v[52:53], v[118:119], v[136:137]
	v_pk_fma_f32 v[24:25], v[56:57], v[62:63], v[40:41] neg_lo:[0,0,1] neg_hi:[0,0,1]
	v_pk_fma_f32 v[30:31], v[56:57], v[66:67], v[30:31] neg_lo:[0,0,1] neg_hi:[0,0,1]
	v_pk_mul_f32 v[40:41], v[38:39], v[72:73]
	v_pk_mul_f32 v[38:39], v[38:39], v[76:77]
	v_pk_add_f32 v[48:49], v[54:55], v[54:55] op_sel:[1,0] op_sel_hi:[1,0]
	v_pk_mul_f32 v[44:45], v[120:121], v[44:45]
	v_pk_add_f32 v[12:13], v[12:13], v[50:51]
	v_pk_add_f32 v[10:11], v[10:11], v[36:37]
	v_pk_fma_f32 v[58:59], v[28:29], v[102:103], v[60:61] neg_lo:[0,0,1] neg_hi:[0,0,1]
	v_pk_fma_f32 v[28:29], v[28:29], v[106:107], v[46:47] neg_lo:[0,0,1] neg_hi:[0,0,1]
	v_pk_add_f32 v[46:47], v[52:53], v[52:53] op_sel:[0,1] op_sel_hi:[0,1] neg_lo:[0,1] neg_hi:[0,1]
	v_pk_mul_f32 v[26:27], v[120:121], v[26:27]
	v_pk_fma_f32 v[36:37], v[42:43], v[70:71], v[40:41] neg_lo:[0,0,1] neg_hi:[0,0,1]
	v_pk_fma_f32 v[38:39], v[42:43], v[74:75], v[38:39] neg_lo:[0,0,1] neg_hi:[0,0,1]
	v_pk_mul_f32 v[40:41], v[48:49], v[80:81]
	v_pk_mul_f32 v[42:43], v[48:49], v[84:85]
	v_pk_add_f32 v[44:45], v[44:45], v[44:45] op_sel:[1,0] op_sel_hi:[1,0]
	v_pk_mul_f32 v[50:51], v[122:123], v[142:143]
	v_pk_add_f32 v[12:13], v[12:13], v[24:25]
	v_pk_add_f32 v[10:11], v[10:11], v[30:31]
	v_pk_add_f32 v[26:27], v[26:27], v[26:27] op_sel:[0,1] op_sel_hi:[0,1] neg_lo:[0,1] neg_hi:[0,1]
	v_pk_mul_f32 v[48:49], v[122:123], v[140:141]
	v_pk_fma_f32 v[24:25], v[46:47], v[78:79], v[40:41] neg_lo:[0,0,1] neg_hi:[0,0,1]
	v_pk_fma_f32 v[30:31], v[46:47], v[82:83], v[42:43] neg_lo:[0,0,1] neg_hi:[0,0,1]
	v_pk_mul_f32 v[40:41], v[44:45], v[88:89]
	v_pk_mul_f32 v[42:43], v[44:45], v[92:93]
	v_pk_add_f32 v[46:47], v[50:51], v[50:51] op_sel:[1,0] op_sel_hi:[1,0]
; __device__ __forceinline__ f32x2 cmul(f32x2 a, f32x2 b) { return (f32x2){a.x * b.x - a.y * b.y, a.x * b.y + a.y * b.x}; }
; __global__ void __launch_bounds__(512, 2) fwd_kernel(Args a) {
;     ...
;         for (size_t i = vt; i < (size_t)NG * 16 * 64; i += VNT) {
;             const int hq = (int)i & 3, h = ((int)i >> 2) & 15, lag = ((int)i >> 6) & 15, g = (int)i >> 10;
;             float s0 = 0.f, s1 = 0.f, s2 = 0.f, s3 = 0.f;
;             const float* crp = c_re + (size_t)(g * NH + h) * NP; const float* cip = c_im + (size_t)(g * NH + h) * NP;
; #pragma unroll 8
;             for (int p = 0; p < NP; ++p) {
;                 const int gp = g * NP + p;
;                 const f32x2 ac = cmul(APW[gp * 17 + lag], (f32x2){crp[p], cip[p]});
;                 const f32x4 b01 = *(const f32x4*)(BBAR + (size_t)gp * NH + 4 * hq), b23 = *(const f32x4*)(BBAR + (size_t)gp * NH + 4 * hq + 2);
;                 s0 += ac.x * b01[0] - ac.y * b01[1]; s1 += ac.x * b01[2] - ac.y * b01[3]; s2 += ac.x * b23[0] - ac.y * b23[1]; s3 += ac.x * b23[2] - ac.y * b23[3];
;             }
	v_pk_add_f32 v[12:13], v[12:13], v[36:37]
	v_pk_add_f32 v[10:11], v[10:11], v[38:39]
	v_pk_add_f32 v[44:45], v[48:49], v[48:49] op_sel:[0,1] op_sel_hi:[0,1] neg_lo:[0,1] neg_hi:[0,1]
	v_pk_fma_f32 v[36:37], v[26:27], v[86:87], v[40:41] neg_lo:[0,0,1] neg_hi:[0,0,1]
	v_pk_fma_f32 v[26:27], v[26:27], v[90:91], v[42:43] neg_lo:[0,0,1] neg_hi:[0,0,1]
	v_pk_mul_f32 v[38:39], v[46:47], v[96:97]
	v_pk_mul_f32 v[40:41], v[46:47], v[100:101]
	v_pk_add_f32 v[12:13], v[12:13], v[24:25]
	v_pk_add_f32 v[10:11], v[10:11], v[30:31]
	v_pk_fma_f32 v[24:25], v[44:45], v[94:95], v[38:39] neg_lo:[0,0,1] neg_hi:[0,0,1]
	v_pk_fma_f32 v[30:31], v[44:45], v[98:99], v[40:41] neg_lo:[0,0,1] neg_hi:[0,0,1]
	v_pk_add_f32 v[12:13], v[12:13], v[36:37]
	v_pk_add_f32 v[10:11], v[10:11], v[26:27]
	v_pk_add_f32 v[12:13], v[12:13], v[24:25]
	v_pk_add_f32 v[10:11], v[10:11], v[30:31]
	v_pk_add_f32 v[12:13], v[12:13], v[58:59]
	v_pk_add_f32 v[10:11], v[10:11], v[28:29]
	v_mov_b32_e32 v124, v158
	v_mov_b32_e32 v125, v162
	v_mov_b32_e32 v126, v162
	v_mov_b32_e32 v127, v158
	v_mov_b32_e32 v158, v163
	v_pk_mul_f32 v[124:125], v[144:145], v[124:125]
	v_pk_mul_f32 v[144:145], v[144:145], v[126:127]
	v_mov_b32_e32 v162, v159
	v_mov_b32_e32 v132, v160
	v_mov_b32_e32 v133, v164
	v_mov_b32_e32 v134, v164
	v_mov_b32_e32 v135, v160
	v_mov_b32_e32 v127, v170
	v_mov_b32_e32 v170, v173
	v_mov_b32_e32 v173, v174
	v_mov_b32_e32 v174, v177
	v_pk_mul_f32 v[158:159], v[234:235], v[158:159]
	v_pk_add_f32 v[144:145], v[144:145], v[144:145] op_sel:[1,0] op_sel_hi:[1,0]
	v_mov_b32_e32 v160, v165
	v_mov_b32_e32 v140, v168
	v_mov_b32_e32 v143, v168
	v_mov_b32_e32 v168, v149
	v_mov_b32_e32 v126, v172
	v_mov_b32_e32 v172, v176
	v_pk_mul_f32 v[162:163], v[234:235], v[162:163]
	v_mov_b32_e32 v176, v180
	v_mov_b32_e32 v177, v178
	v_mov_b32_e32 v178, v181
	v_mov_b32_e32 v180, v184
	v_mov_b32_e32 v181, v182
	v_mov_b32_e32 v182, v185
	v_mov_b32_e32 v184, v188
	v_mov_b32_e32 v185, v186
	v_mov_b32_e32 v186, v189
	v_mov_b32_e32 v188, v192
	v_mov_b32_e32 v189, v190
	v_mov_b32_e32 v190, v193
	v_mov_b32_e32 v192, v196
	v_mov_b32_e32 v193, v194
	v_mov_b32_e32 v194, v197
	v_mov_b32_e32 v196, v200
	v_mov_b32_e32 v197, v198
	v_mov_b32_e32 v198, v201
	v_mov_b32_e32 v200, v204
	v_mov_b32_e32 v201, v202
	v_mov_b32_e32 v202, v205
	v_mov_b32_e32 v204, v208
	v_mov_b32_e32 v205, v206
	v_mov_b32_e32 v206, v209
	v_mov_b32_e32 v208, v212
	v_mov_b32_e32 v209, v210
	v_mov_b32_e32 v210, v213
	v_mov_b32_e32 v212, v216
	v_mov_b32_e32 v213, v214
	v_mov_b32_e32 v214, v217
	v_mov_b32_e32 v216, v220
	v_mov_b32_e32 v217, v218
	v_mov_b32_e32 v218, v221
	v_mov_b32_e32 v220, v224
	v_mov_b32_e32 v221, v222
	v_mov_b32_e32 v222, v225
	v_mov_b32_e32 v224, v228
	v_mov_b32_e32 v225, v226
	v_mov_b32_e32 v226, v229
	v_mov_b32_e32 v228, v232
	v_mov_b32_e32 v229, v230
	v_mov_b32_e32 v230, v233
	v_pk_add_f32 v[232:233], v[124:125], v[124:125] op_sel:[0,1] op_sel_hi:[0,1] neg_lo:[0,1] neg_hi:[0,1]
	v_pk_add_f32 v[158:159], v[158:159], v[158:159] op_sel:[1,0] op_sel_hi:[1,0]
	v_pk_mul_f32 v[234:235], v[150:151], v[132:133]
	v_pk_mul_f32 v[150:151], v[150:151], v[134:135]
	v_pk_mul_f32 v[170:171], v[144:145], v[170:171]
	v_pk_mul_f32 v[144:145], v[144:145], v[174:175]
	v_mov_b32_e32 v164, v161
	v_mov_b32_e32 v138, v146
	v_mov_b32_e32 v139, v166
	v_mov_b32_e32 v141, v148
	v_mov_b32_e32 v142, v148
	v_mov_b32_e32 v148, v169
	v_pk_mul_f32 v[168:169], v[240:241], v[168:169]
	v_pk_add_f32 v[162:163], v[162:163], v[162:163] op_sel:[0,1] op_sel_hi:[0,1] neg_lo:[0,1] neg_hi:[0,1]
	v_pk_mul_f32 v[174:175], v[158:159], v[178:179]
	v_pk_mul_f32 v[158:159], v[158:159], v[182:183]
	v_pk_add_f32 v[150:151], v[150:151], v[150:151] op_sel:[1,0] op_sel_hi:[1,0]
	v_pk_mul_f32 v[160:161], v[238:239], v[160:161]
	v_pk_fma_f32 v[170:171], v[232:233], v[126:127], v[170:171] neg_lo:[0,0,1] neg_hi:[0,0,1]
	v_pk_fma_f32 v[144:145], v[232:233], v[172:173], v[144:145] neg_lo:[0,0,1] neg_hi:[0,0,1]
	v_mov_b32_e32 v136, v166
	v_mov_b32_e32 v137, v146
	v_mov_b32_e32 v166, v147
	v_pk_mul_f32 v[148:149], v[240:241], v[148:149]
	v_pk_add_f32 v[168:169], v[168:169], v[168:169] op_sel:[1,0] op_sel_hi:[1,0]
	v_pk_add_f32 v[178:179], v[234:235], v[234:235] op_sel:[0,1] op_sel_hi:[0,1] neg_lo:[0,1] neg_hi:[0,1]
	v_pk_mul_f32 v[164:165], v[238:239], v[164:165]
	v_pk_fma_f32 v[172:173], v[162:163], v[176:177], v[174:175] neg_lo:[0,0,1] neg_hi:[0,0,1]
; __device__ __forceinline__ f32x2 cmul(f32x2 a, f32x2 b) { return (f32x2){a.x * b.x - a.y * b.y, a.x * b.y + a.y * b.x}; }
; __global__ void __launch_bounds__(512, 2) fwd_kernel(Args a) {
;     ...
;             for (int p = 0; p < NP; ++p) {
;                 const int gp = g * NP + p;
;                 const f32x2 ac = cmul(APW[gp * 17 + lag], (f32x2){crp[p], cip[p]});
;                 const f32x4 b01 = *(const f32x4*)(BBAR + (size_t)gp * NH + 4 * hq), b23 = *(const f32x4*)(BBAR + (size_t)gp * NH + 4 * hq + 2);
;                 s0 += ac.x * b01[0] - ac.y * b01[1]; s1 += ac.x * b01[2] - ac.y * b01[3]; s2 += ac.x * b23[0] - ac.y * b23[1]; s3 += ac.x * b23[2] - ac.y * b23[3];
;             }
;             if (lag == 0 && (h >> 2) == hq) { const float dd = s5_d[g * NH + h]; if ((h & 3) == 0) s0 += dd; else if ((h & 3) == 1) s1 += dd; else if ((h & 3) == 2) s2 += dd; else s3 += dd; }
	v_pk_fma_f32 v[158:159], v[162:163], v[180:181], v[158:159] neg_lo:[0,0,1] neg_hi:[0,0,1]
	v_pk_mul_f32 v[162:163], v[150:151], v[186:187]
	v_pk_mul_f32 v[150:151], v[150:151], v[190:191]
	v_pk_add_f32 v[160:161], v[160:161], v[160:161] op_sel:[1,0] op_sel_hi:[1,0]
	v_pk_mul_f32 v[176:177], v[242:243], v[138:139]
	v_pk_add_f32 v[12:13], v[12:13], v[170:171]
	v_pk_add_f32 v[10:11], v[10:11], v[144:145]
	v_mov_b32_e32 v146, v167
	v_pk_add_f32 v[148:149], v[148:149], v[148:149] op_sel:[0,1] op_sel_hi:[0,1] neg_lo:[0,1] neg_hi:[0,1]
	v_pk_mul_f32 v[182:183], v[168:169], v[226:227]
	v_pk_mul_f32 v[168:169], v[168:169], v[230:231]
	v_pk_add_f32 v[164:165], v[164:165], v[164:165] op_sel:[0,1] op_sel_hi:[0,1] neg_lo:[0,1] neg_hi:[0,1]
	v_pk_mul_f32 v[174:175], v[242:243], v[136:137]
	v_pk_fma_f32 v[144:145], v[178:179], v[184:185], v[162:163] neg_lo:[0,0,1] neg_hi:[0,0,1]
	v_pk_fma_f32 v[150:151], v[178:179], v[188:189], v[150:151] neg_lo:[0,0,1] neg_hi:[0,0,1]
	v_pk_mul_f32 v[162:163], v[160:161], v[194:195]
	v_pk_mul_f32 v[160:161], v[160:161], v[198:199]
	v_pk_add_f32 v[170:171], v[176:177], v[176:177] op_sel:[1,0] op_sel_hi:[1,0]
	v_pk_mul_f32 v[166:167], v[244:245], v[166:167]
	v_pk_add_f32 v[12:13], v[12:13], v[172:173]
	v_pk_add_f32 v[10:11], v[10:11], v[158:159]
	v_pk_fma_f32 v[180:181], v[148:149], v[224:225], v[182:183] neg_lo:[0,0,1] neg_hi:[0,0,1]
	v_pk_fma_f32 v[148:149], v[148:149], v[228:229], v[168:169] neg_lo:[0,0,1] neg_hi:[0,0,1]
	v_pk_add_f32 v[168:169], v[174:175], v[174:175] op_sel:[0,1] op_sel_hi:[0,1] neg_lo:[0,1] neg_hi:[0,1]
	v_pk_mul_f32 v[146:147], v[244:245], v[146:147]
	v_pk_fma_f32 v[158:159], v[164:165], v[192:193], v[162:163] neg_lo:[0,0,1] neg_hi:[0,0,1]
	v_pk_fma_f32 v[160:161], v[164:165], v[196:197], v[160:161] neg_lo:[0,0,1] neg_hi:[0,0,1]
	v_pk_mul_f32 v[162:163], v[170:171], v[202:203]
	v_pk_mul_f32 v[164:165], v[170:171], v[206:207]
	v_pk_add_f32 v[166:167], v[166:167], v[166:167] op_sel:[1,0] op_sel_hi:[1,0]
	v_pk_mul_f32 v[172:173], v[246:247], v[142:143]
	v_pk_add_f32 v[12:13], v[12:13], v[144:145]
	v_pk_add_f32 v[10:11], v[10:11], v[150:151]
	v_pk_add_f32 v[146:147], v[146:147], v[146:147] op_sel:[0,1] op_sel_hi:[0,1] neg_lo:[0,1] neg_hi:[0,1]
	v_pk_mul_f32 v[170:171], v[246:247], v[140:141]
	v_pk_fma_f32 v[144:145], v[168:169], v[200:201], v[162:163] neg_lo:[0,0,1] neg_hi:[0,0,1]
	v_pk_fma_f32 v[150:151], v[168:169], v[204:205], v[164:165] neg_lo:[0,0,1] neg_hi:[0,0,1]
	v_pk_mul_f32 v[162:163], v[166:167], v[210:211]
	v_pk_mul_f32 v[164:165], v[166:167], v[214:215]
	v_pk_add_f32 v[168:169], v[172:173], v[172:173] op_sel:[1,0] op_sel_hi:[1,0]
	v_pk_add_f32 v[12:13], v[12:13], v[158:159]
	v_pk_add_f32 v[10:11], v[10:11], v[160:161]
	v_pk_add_f32 v[166:167], v[170:171], v[170:171] op_sel:[0,1] op_sel_hi:[0,1] neg_lo:[0,1] neg_hi:[0,1]
	v_pk_fma_f32 v[158:159], v[146:147], v[208:209], v[162:163] neg_lo:[0,0,1] neg_hi:[0,0,1]
	v_pk_fma_f32 v[146:147], v[146:147], v[212:213], v[164:165] neg_lo:[0,0,1] neg_hi:[0,0,1]
	v_pk_mul_f32 v[160:161], v[168:169], v[218:219]
	v_pk_mul_f32 v[162:163], v[168:169], v[222:223]
	v_pk_add_f32 v[12:13], v[12:13], v[144:145]
	v_pk_add_f32 v[10:11], v[10:11], v[150:151]
	v_pk_fma_f32 v[144:145], v[166:167], v[216:217], v[160:161] neg_lo:[0,0,1] neg_hi:[0,0,1]
	v_pk_fma_f32 v[150:151], v[166:167], v[220:221], v[162:163] neg_lo:[0,0,1] neg_hi:[0,0,1]
	v_pk_add_f32 v[12:13], v[12:13], v[158:159]
	v_pk_add_f32 v[10:11], v[10:11], v[146:147]
	v_pk_add_f32 v[12:13], v[12:13], v[144:145]
	v_pk_add_f32 v[10:11], v[10:11], v[150:151]
	v_pk_add_f32 v[12:13], v[12:13], v[180:181]
	v_pk_add_f32 v[10:11], v[10:11], v[148:149]
	s_cbranch_scc0 .LBB0_198
	v_and_b32_e32 v4, 15, v34
	v_cmp_eq_u32_e32 vcc, 0, v4
	v_bfe_u32 v4, v33, 2, 2
	v_cmp_eq_u32_e64 s[8:9], v4, v3
	s_and_b64 s[4:5], vcc, s[8:9]
	s_and_saveexec_b64 s[8:9], s[4:5]
	s_cbranch_execz .LBB0_196
	v_and_b32_e32 v4, 15, v33
	v_or_b32_e32 v4, v32, v4
	v_lshlrev_b32_e32 v4, 2, v4
	global_load_dword v4, v4, s[24:25]
	v_bfe_u32 v16, v8, 2, 2
	v_cmp_lt_i32_e32 vcc, 1, v16
	s_and_saveexec_b64 s[4:5], vcc
	s_xor_b64 s[66:67], exec, s[4:5]
	s_cbranch_execz .LBB0_206
	v_cmp_lt_i32_e32 vcc, 2, v16
	s_and_saveexec_b64 s[4:5], vcc
	s_xor_b64 s[68:69], exec, s[4:5]
	s_cbranch_execz .LBB0_203
	s_waitcnt vmcnt(0)
	v_add_f32_e32 v14, v10, v4
	v_mov_b32_e32 v15, v11

; __device__ __forceinline__ unsigned cvt_pk_bf16(float lo, float hi) { unsigned r; asm volatile("v_cvt_pk_bf16_f32 %0, %1, %2" : "=v"(r) : "v"(lo), "v"(hi)); return r; }
; __device__ __forceinline__ f32x2 cmul(f32x2 a, f32x2 b) { return (f32x2){a.x * b.x - a.y * b.y, a.x * b.y + a.y * b.x}; }
; __global__ void __launch_bounds__(512, 2) fwd_kernel(Args a) {
;     ...
;         for (size_t i = vt; i < (size_t)NG * NP * 16; i += VNT) {
;             const int j = (int)i & 15, p = ((int)i >> 4) & 63, g = (int)i >> 10; const int gp = g * NP + p;
;             const f32x2 cf = APW[gp * 17 + 15 - j];
;             unsigned wre[8], wim[8];
; #pragma unroll
;             for (int h = 0; h < NH; h += 2) {
;                 const f32x4 b2 = *(const f32x4*)(BBAR + (size_t)gp * NH + h);
;                 const f32x2 v0 = cmul(cf, (f32x2){b2[0], b2[1]}), v1 = cmul(cf, (f32x2){b2[2], b2[3]});
;                 wre[h >> 1] = cvt_pk_bf16(v0.x, v1.x); wim[h >> 1] = cvt_pk_bf16(v0.y, v1.y);
;             }
;             bf16* w2r = W2 + ((size_t)(g * 128 + 2 * p) * 256 + j * 16);
;             *(v4u*)(w2r) = (v4u){wre[0], wre[1], wre[2], wre[3]}; *(v4u*)(w2r + 8) = (v4u){wre[4], wre[5], wre[6], wre[7]};
;             *(v4u*)(w2r + 256) = (v4u){wim[0], wim[1], wim[2], wim[3]}; *(v4u*)(w2r + 264) = (v4u){wim[4], wim[5], wim[6], wim[7]};
;         }
.LBB0_214:
	v_bfe_u32 v32, v6, 4, 6
	v_lshrrev_b32_e32 v33, 10, v6
	s_waitcnt vmcnt(1)
	v_lshl_or_b32 v4, v33, 6, v32
	v_mad_u64_u32 v[8:9], s[0:1], v4, 17, v[2:3]
	v_mov_b32_e32 v9, v5
	v_lshlrev_b32_e32 v4, 4, v4
	v_lshl_add_u64 v[12:13], v[8:9], 3, s[16:17]
	v_lshl_add_u64 v[26:27], v[4:5], 3, s[24:25]
	global_load_dwordx2 v[28:29], v[12:13], off
	global_load_dwordx4 v[8:11], v[26:27], off
	global_load_dwordx4 v[40:43], v[26:27], off offset:16
	global_load_dwordx4 v[44:47], v[26:27], off offset:32
	global_load_dwordx4 v[48:51], v[26:27], off offset:48
	global_load_dwordx4 v[52:55], v[26:27], off offset:64
	global_load_dwordx4 v[56:59], v[26:27], off offset:80
	global_load_dwordx4 v[60:63], v[26:27], off offset:96
	global_load_dwordx4 v[64:67], v[26:27], off offset:112
	v_lshl_add_u64 v[6:7], v[6:7], 0, s[18:19]
	v_cmp_lt_u64_e32 vcc, s[42:43], v[6:7]
	s_or_b64 s[26:27], vcc, s[26:27]
	s_waitcnt vmcnt(7)
	v_pk_mul_f32 v[12:13], v[28:29], v[8:9]
	v_pk_mul_f32 v[8:9], v[28:29], v[8:9] op_sel:[0,1] op_sel_hi:[1,0]
	v_pk_mul_f32 v[14:15], v[28:29], v[10:11]
	v_pk_mul_f32 v[10:11], v[28:29], v[10:11] op_sel:[0,1] op_sel_hi:[1,0]
	v_add_f32_e32 v9, v8, v9
	v_sub_f32_e32 v8, v14, v15
	v_sub_f32_e32 v4, v12, v13
	v_add_f32_e32 v10, v10, v11
	v_cvt_pk_bf16_f32 v8, v4, v8
	v_cvt_pk_bf16_f32 v12, v9, v10
	s_waitcnt vmcnt(6)
	v_pk_mul_f32 v[18:19], v[28:29], v[42:43]
	v_pk_mul_f32 v[10:11], v[28:29], v[40:41]
	v_pk_mul_f32 v[14:15], v[28:29], v[40:41] op_sel:[0,1] op_sel_hi:[1,0]
	v_pk_mul_f32 v[16:17], v[28:29], v[42:43] op_sel:[0,1] op_sel_hi:[1,0]
	v_sub_f32_e32 v9, v18, v19
	v_sub_f32_e32 v4, v10, v11
	v_add_f32_e32 v10, v14, v15
	v_add_f32_e32 v11, v16, v17
	v_cvt_pk_bf16_f32 v9, v4, v9
	v_cvt_pk_bf16_f32 v13, v10, v11
	s_waitcnt vmcnt(5)
	v_pk_mul_f32 v[10:11], v[28:29], v[44:45]
	v_pk_mul_f32 v[14:15], v[28:29], v[44:45] op_sel:[0,1] op_sel_hi:[1,0]
	v_pk_mul_f32 v[18:19], v[28:29], v[46:47]
	v_pk_mul_f32 v[16:17], v[28:29], v[46:47] op_sel:[0,1] op_sel_hi:[1,0]
	v_sub_f32_e32 v4, v10, v11
	v_add_f32_e32 v11, v14, v15
	v_sub_f32_e32 v10, v18, v19
	v_add_f32_e32 v14, v16, v17
	v_cvt_pk_bf16_f32 v10, v4, v10
	v_cvt_pk_bf16_f32 v14, v11, v14
	s_waitcnt vmcnt(4)
	v_pk_mul_f32 v[20:21], v[28:29], v[48:49]
	v_pk_mul_f32 v[16:17], v[28:29], v[48:49] op_sel:[0,1] op_sel_hi:[1,0]
	v_pk_mul_f32 v[22:23], v[28:29], v[50:51]
	v_pk_mul_f32 v[18:19], v[28:29], v[50:51] op_sel:[0,1] op_sel_hi:[1,0]
	v_add_f32_e32 v15, v16, v17
	v_sub_f32_e32 v11, v22, v23
	v_add_f32_e32 v16, v18, v19
	v_sub_f32_e32 v4, v20, v21
	v_cvt_pk_bf16_f32 v11, v4, v11
	v_cvt_pk_bf16_f32 v15, v15, v16
	s_waitcnt vmcnt(3)
	v_pk_mul_f32 v[20:21], v[28:29], v[52:53]
	v_pk_mul_f32 v[16:17], v[28:29], v[52:53] op_sel:[0,1] op_sel_hi:[1,0]
	v_pk_mul_f32 v[22:23], v[28:29], v[54:55]
	v_pk_mul_f32 v[18:19], v[28:29], v[54:55] op_sel:[0,1] op_sel_hi:[1,0]
	v_add_f32_e32 v17, v16, v17
	v_sub_f32_e32 v16, v22, v23
	v_sub_f32_e32 v4, v20, v21
	v_add_f32_e32 v18, v18, v19
	v_cvt_pk_bf16_f32 v16, v4, v16
	v_cvt_pk_bf16_f32 v20, v17, v18
	s_waitcnt vmcnt(2)
	v_pk_mul_f32 v[30:31], v[28:29], v[58:59]
	v_pk_mul_f32 v[18:19], v[28:29], v[56:57]
	v_pk_mul_f32 v[22:23], v[28:29], v[56:57] op_sel:[0,1] op_sel_hi:[1,0]
	v_pk_mul_f32 v[24:25], v[28:29], v[58:59] op_sel:[0,1] op_sel_hi:[1,0]
	v_sub_f32_e32 v17, v30, v31
	v_sub_f32_e32 v4, v18, v19
	v_add_f32_e32 v18, v22, v23
	v_add_f32_e32 v19, v24, v25
	v_cvt_pk_bf16_f32 v17, v4, v17
	v_cvt_pk_bf16_f32 v21, v18, v19
	s_waitcnt vmcnt(1)
	v_pk_mul_f32 v[18:19], v[28:29], v[60:61]
	v_pk_mul_f32 v[22:23], v[28:29], v[60:61] op_sel:[0,1] op_sel_hi:[1,0]
	v_pk_mul_f32 v[30:31], v[28:29], v[62:63]
	v_pk_mul_f32 v[24:25], v[28:29], v[62:63] op_sel:[0,1] op_sel_hi:[1,0]
	v_sub_f32_e32 v4, v18, v19
	v_add_f32_e32 v19, v22, v23
	v_sub_f32_e32 v18, v30, v31
	v_add_f32_e32 v22, v24, v25
	v_cvt_pk_bf16_f32 v18, v4, v18
	v_cvt_pk_bf16_f32 v22, v19, v22
	v_lshlrev_b32_e32 v4, 15, v33
	v_lshlrev_b32_e32 v19, 9, v32
	v_or3_b32 v4, v19, v4, v3
	v_lshlrev_b32_e32 v4, 1, v4
	s_waitcnt vmcnt(0)
	v_pk_mul_f32 v[30:31], v[28:29], v[64:65]
	v_pk_mul_f32 v[24:25], v[28:29], v[64:65] op_sel:[0,1] op_sel_hi:[1,0]
	v_pk_mul_f32 v[32:33], v[28:29], v[66:67]
	v_pk_mul_f32 v[26:27], v[28:29], v[66:67] op_sel:[0,1] op_sel_hi:[1,0]
	v_sub_f32_e32 v19, v30, v31
	v_add_f32_e32 v23, v24, v25
	v_sub_f32_e32 v24, v32, v33
	v_add_f32_e32 v25, v26, v27
	v_cvt_pk_bf16_f32 v19, v19, v24
	v_cvt_pk_bf16_f32 v23, v23, v25
	global_store_dwordx4 v4, v[8:11], s[8:9]
	global_store_dwordx4 v4, v[12:15], s[8:9] offset:512
	global_store_dwordx4 v4, v[16:19], s[8:9] offset:16
	global_store_dwordx4 v4, v[20:23], s[8:9] offset:528
	s_andn2_b64 exec, exec, s[26:27]
	s_cbranch_execnz .LBB0_214
